# P3: folded memory cross-attention weight products moved to workgroups 128-255 (which have one q-up tile less)
# speedup vs baseline: 1.0024x; 1.0024x over previous
.LBB0_604:
	s_and_b32 s26, s87, 3
	s_xor_b32 s33, s87, 0x80
	s_ashr_i32 s33, s33, 2
	s_lshl_b32 s27, s26, 19
	s_cmp_gt_i32 s33, 15
	s_mov_b64 s[0:1], -1
	s_cbranch_scc0 .LBB0_620
	s_cmp_gt_u32 s33, 31
	s_cbranch_scc1 .LBB0_637
	s_add_i32 s0, s33, -16
	s_lshr_b32 s34, s0, 3
	s_mov_b32 s35, 0
	s_lshl_b64 s[0:1], s[34:35], 20
	s_lshl_b32 s34, s34, 1
	s_bfe_u32 s17, s33, 0x10002
	s_and_b32 s16, s33, 3
	s_lshl_b64 s[2:3], s[34:35], 20
	s_add_u32 s0, s8, s0
	s_addc_u32 s1, s9, s1
	s_lshl_b32 s4, s17, 19
	s_add_u32 s0, s0, s4
	s_addc_u32 s1, s1, 0
	s_lshl_b32 s4, s16, 9
	s_add_u32 s0, s0, s4
	s_addc_u32 s1, s1, 0
	s_add_u32 s0, s0, 0x900000
	s_addc_u32 s1, s1, 0
	s_add_u32 s2, s8, s2
	s_addc_u32 s3, s9, s3
	v_mbcnt_lo_u32_b32 v4, -1, 0
	v_mbcnt_hi_u32_b32 v4, -1, v4
	s_add_u32 s2, s2, s4
	v_add_u32_e32 v0, s86, v4
	v_ashrrev_i32_e32 v2, 31, v0
	s_addc_u32 s3, s3, 0
	v_lshrrev_b32_e32 v2, 26, v2
	s_add_u32 s56, s2, 0x1b00000
	v_readfirstlane_b32 s2, v0
	v_lshlrev_b32_e32 v1, 4, v0
	v_add_u32_e32 v2, v0, v2
	v_bfe_i32 v0, v0, 27, 1
	v_lshrrev_b32_e32 v0, 22, v0
	v_add_u32_e32 v0, v1, v0
	v_and_b32_e32 v0, 0xfffffc00, v0
	v_sub_u32_e32 v0, v1, v0
	v_lshrrev_b32_e32 v1, 4, v0
	v_bitop3_b32 v0, v1, v0, 32 bitop3:0x6c
	v_ashrrev_i32_e32 v3, 31, v0
	v_ashrrev_i32_e32 v2, 6, v2
	v_lshrrev_b32_e32 v3, 26, v3
	v_lshlrev_b32_e32 v1, 3, v2
	v_add_u32_e32 v3, v0, v3
	v_and_b32_e32 v1, -16, v1
	v_ashrrev_i32_e32 v5, 6, v3
	v_and_b32_e32 v3, 0xc0, v3
	v_add_u32_e32 v1, v5, v1
	v_sub_u32_e32 v0, v0, v3
	v_mov_b32_e32 v3, 1
	s_addc_u32 s57, s3, 0
	s_ashr_i32 s30, s2, 6
	v_lshlrev_b32_e32 v2, 5, v2
	v_ashrrev_i16_sdwa v0, v3, sext(v0) dst_sel:DWORD dst_unused:UNUSED_PAD src0_sel:DWORD src1_sel:BYTE_0
	v_lshlrev_b32_e32 v3, 1, v1
	v_lshrrev_b32_e32 v6, 2, v1
	v_and_b32_e32 v5, 3, v5
	s_mov_b32 s4, 0x1fffe0
	s_ashr_i32 s3, s2, 8
	v_and_b32_e32 v2, 32, v2
	v_bfe_i32 v0, v0, 0, 16
	v_and_b32_e32 v3, 24, v3
	v_and_b32_e32 v6, 4, v6
	v_and_or_b32 v5, v1, s4, v5
	s_lshl_b32 s58, s30, 10
	v_or3_b32 v3, v5, v3, v6
	v_add_lshl_u32 v0, v2, v0, 1
	s_add_u32 s44, s56, s27
	v_lshl_add_u32 v130, v3, 11, v0
	s_addc_u32 s45, s57, 0
	v_mov_b32_e32 v131, 0
	s_add_i32 s59, s58, 0
	v_lshl_add_u32 v128, v1, 11, v0
	v_lshl_add_u64 v[0:1], s[44:45], 0, v[130:131]
	s_add_i32 m0, s59, 0x10000
	s_mov_b64 s[4:5], 0x20000
	global_load_lds_dwordx4 v130, s[44:45]
	v_lshl_add_u64 v[2:3], v[0:1], 0, s[4:5]
	s_add_i32 m0, s59, 0x12000
	s_mov_b64 s[6:7], 0x40000
	global_load_lds_dwordx4 v[2:3], off
	v_lshl_add_u64 v[2:3], v[0:1], 0, s[6:7]
	s_add_i32 m0, s59, 0x14000
	s_mov_b64 s[12:13], 0x60000
	global_load_lds_dwordx4 v[2:3], off
	v_lshl_add_u64 v[2:3], v[0:1], 0, s[12:13]
	s_add_i32 m0, s59, 0x16000
	v_mov_b32_e32 v129, v131
	global_load_lds_dwordx4 v[2:3], off
	v_lshl_add_u64 v[2:3], s[0:1], 0, v[128:129]
	s_mov_b32 m0, s59
	s_add_i32 s62, s59, 0x2000
	global_load_lds_dwordx4 v128, s[0:1]
	v_lshl_add_u64 v[6:7], v[2:3], 0, s[4:5]
	s_mov_b32 m0, s62
	s_add_i32 s65, s59, 0x4000
	global_load_lds_dwordx4 v[6:7], off
	v_lshl_add_u64 v[6:7], v[2:3], 0, s[6:7]
	s_mov_b32 m0, s65
	s_add_i32 s66, s59, 0x6000
	global_load_lds_dwordx4 v[6:7], off
	v_lshl_add_u64 v[6:7], v[2:3], 0, s[12:13]
	s_mov_b32 m0, s66
	s_cmp_eq_u32 s3, 1
	global_load_lds_dwordx4 v[6:7], off
	s_cselect_b64 s[14:15], -1, 0
	s_cmp_lg_u32 s3, 1
	s_cbranch_scc1 .LBB0_608
	s_barrier

.LBB0_621:
	s_xor_b32 s0, s87, 0x80
	s_ashr_i32 s0, s0, 5
	s_lshl_b32 s2, s0, 1
	s_ashr_i32 s3, s2, 31
	s_lshl_b32 s1, s33, 8
	s_lshl_b64 s[4:5], s[2:3], 20
	s_and_b32 s3, s1, 0x300
	s_ashr_i32 s1, s0, 31
	s_bfe_u32 s16, s87, 0x10004
	s_lshl_b64 s[0:1], s[0:1], 20
	s_add_u32 s4, s8, s4
	s_addc_u32 s5, s9, s5
	s_lshl_b32 s17, s3, 1
	s_add_u32 s3, s4, s17
	s_addc_u32 s4, s5, 0
	s_add_u32 s33, s3, 0x2700000
	s_addc_u32 s56, s4, 0
	v_mbcnt_lo_u32_b32 v4, -1, 0
	v_mbcnt_hi_u32_b32 v4, -1, v4
	s_add_u32 s0, s8, s0
	v_add_u32_e32 v0, s86, v4
	v_ashrrev_i32_e32 v2, 31, v0
	s_addc_u32 s1, s9, s1
	s_lshl_b32 s3, s16, 19
	v_lshrrev_b32_e32 v2, 26, v2
	s_add_u32 s0, s0, s3
	v_readfirstlane_b32 s3, v0
	v_lshlrev_b32_e32 v1, 4, v0
	v_add_u32_e32 v2, v0, v2
	v_bfe_i32 v0, v0, 27, 1
	v_lshrrev_b32_e32 v0, 22, v0
	v_add_u32_e32 v0, v1, v0
	v_and_b32_e32 v0, 0xfffffc00, v0
	v_sub_u32_e32 v0, v1, v0
	v_lshrrev_b32_e32 v1, 4, v0
	v_bitop3_b32 v0, v1, v0, 32 bitop3:0x6c
	v_ashrrev_i32_e32 v3, 31, v0
	s_addc_u32 s1, s1, 0
	v_ashrrev_i32_e32 v2, 6, v2
	v_lshrrev_b32_e32 v3, 26, v3
	s_add_u32 s0, s0, s17
	v_lshlrev_b32_e32 v1, 3, v2
	v_add_u32_e32 v3, v0, v3
	s_addc_u32 s1, s1, 0
	v_and_b32_e32 v1, -16, v1
	v_ashrrev_i32_e32 v5, 6, v3
	v_and_b32_e32 v3, 0xc0, v3
	s_add_u32 s0, s0, 0xb00000
	v_add_u32_e32 v1, v5, v1
	v_sub_u32_e32 v0, v0, v3
	v_mov_b32_e32 v3, 1
	s_addc_u32 s1, s1, 0
	s_ashr_i32 s31, s3, 6
	v_lshlrev_b32_e32 v2, 5, v2
	v_ashrrev_i16_sdwa v0, v3, sext(v0) dst_sel:DWORD dst_unused:UNUSED_PAD src0_sel:DWORD src1_sel:BYTE_0
	v_lshlrev_b32_e32 v3, 1, v1
	v_lshrrev_b32_e32 v6, 2, v1
	v_and_b32_e32 v5, 3, v5
	s_mov_b32 s4, 0x1fffe0
	s_ashr_i32 s30, s3, 8
	v_and_b32_e32 v2, 32, v2
	v_bfe_i32 v0, v0, 0, 16
	v_and_b32_e32 v3, 24, v3
	v_and_b32_e32 v6, 4, v6
	v_and_or_b32 v5, v1, s4, v5
	s_lshl_b32 s57, s31, 10
	v_or3_b32 v3, v5, v3, v6
	v_add_lshl_u32 v0, v2, v0, 1
	s_add_u32 s44, s33, s27
	v_lshl_add_u32 v130, v3, 11, v0
	s_addc_u32 s45, s56, 0
	v_mov_b32_e32 v131, 0
	s_add_i32 s27, s57, 0
	v_lshl_add_u32 v128, v1, 11, v0
	v_lshl_add_u64 v[0:1], s[0:1], 0, v[130:131]
	s_add_i32 m0, s27, 0x10000
	s_mov_b64 s[4:5], 0x20000
	global_load_lds_dwordx4 v130, s[0:1]
	v_lshl_add_u64 v[2:3], v[0:1], 0, s[4:5]
	s_add_i32 m0, s27, 0x12000
	s_mov_b64 s[6:7], 0x40000
	global_load_lds_dwordx4 v[2:3], off
	v_lshl_add_u64 v[2:3], v[0:1], 0, s[6:7]
	s_add_i32 m0, s27, 0x14000
	s_mov_b64 s[12:13], 0x60000
	global_load_lds_dwordx4 v[2:3], off
	v_lshl_add_u64 v[2:3], v[0:1], 0, s[12:13]
	s_add_i32 m0, s27, 0x16000
	v_mov_b32_e32 v129, v131
	global_load_lds_dwordx4 v[2:3], off
	v_lshl_add_u64 v[2:3], s[44:45], 0, v[128:129]
	s_mov_b32 m0, s27
	s_add_i32 s58, s27, 0x2000
	global_load_lds_dwordx4 v128, s[44:45]
	v_lshl_add_u64 v[6:7], v[2:3], 0, s[4:5]
	s_mov_b32 m0, s58
	s_add_i32 s59, s27, 0x4000
	global_load_lds_dwordx4 v[6:7], off
	v_lshl_add_u64 v[6:7], v[2:3], 0, s[6:7]
	s_mov_b32 m0, s59
	s_add_i32 s62, s27, 0x6000
	global_load_lds_dwordx4 v[6:7], off
	v_lshl_add_u64 v[6:7], v[2:3], 0, s[12:13]
	s_mov_b32 m0, s62
	s_cmp_eq_u32 s30, 1
	global_load_lds_dwordx4 v[6:7], off
	s_cselect_b64 s[14:15], -1, 0
	s_cmp_lg_u32 s30, 1
	s_mov_b32 s72, 0
	s_cbranch_scc1 .LBB0_623
	s_barrier
